# P8: SwiGLU epilogue software-pipelined across units: the last 2 row-blocks of a unit's epilogue run inside the MFMA gaps of the next unit's peeled first k-iteration (phases that do not touch those acc
# baseline (speedup 1.0000x reference)
; #define PG8_STAGE(bufoff, gbase, voff) do { _Pragma("unroll") for (int _i = 0; _i < 2; ++_i) \
;         __builtin_amdgcn_global_load_lds((const unsigned*)((const char*)(gbase) + (voff)[_i]), (PG8_LAS unsigned*)(lds + (bufoff) + ldsw + _i * 8192), 16, 0, 0); } while (0)
; #define PG8_WAIT_V(n) asm volatile("s_waitcnt vmcnt(" #n ")" ::: "memory")
; #define PG8_BAR __builtin_amdgcn_s_barrier()
; template <class Epi, class Sched>
; __device__ __forceinline__ void gemm_phase(PG8_LAS unsigned char* lds, PG8_LAS unsigned char* xl, const Gemm g, const Sched& S, const Epi& E) {
;     ...
;     for (int i = 0; i < 2; ++i) { int R, C; stage_rc(tid * 16 + i * 8192, R, C); const int Rb = (R & ~31) + perm32(R & 31);
;         voffA[i] = (unsigned)(R * g.lda + C) * 2u; voffB[i] = (unsigned)(Rb * g.ldb + C) * 2u; }
;     const size_t kstep = (size_t)(BK * 2);
;     const size_t hsA = (size_t)HALF * g.lda * 2, hsB = (size_t)HALF * g.ldb * 2;
;     const unsigned ldsw = (unsigned)wid * 1024u;
;     const int aoff = lds_byte(wr * 64 + fr, fq * 8), boff = lds_byte(wc * 32 + fr, fq * 8);
;     ...
;     Unit cur, nxt; int ui = 0;
;     if (!S.next(0, cur)) return;
;     Acc acc;
; #pragma unroll
;     for (int a = 0; a < 2; ++a)
; #pragma unroll
;         for (int b = 0; b < 2; ++b)
; #pragma unroll
;             for (int m = 0; m < 4; ++m)
; #pragma unroll
;                 for (int n = 0; n < 2; ++n) acc[a][b][m][n] = (f32x4){0.f, 0.f, 0.f, 0.f};
;     bf16x8 At[4][2], B0[2][2], B1[2][2];
;     const char* cA = (const char*)g.A + cur.aoff; const char* cB = (const char*)g.Bt + cur.boff;
;     PG8_STAGE(PG8_SB(0, 0), cB, voffB); PG8_STAGE(PG8_SB(0, 1), cB + hsB, voffB); PG8_STAGE(PG8_SA(0, 0), cA, voffA); PG8_STAGE(PG8_SA(0, 1), cA + hsA, voffA);
;     if (wr == 1) PG8_BAR;
;     PG8_WAIT_V(2); PG8_BAR;
;     PG8_STAGE(PG8_SB(1, 0), cB + kstep, voffB); PG8_STAGE(PG8_SA(1, 0), cA + kstep, voffA); PG8_STAGE(PG8_SB(1, 1), cB + hsB + kstep, voffB);
;     PG8_WAIT_V(6); PG8_BAR;
.LBB0_819:
	s_sext_i32_i16 s8, s8
	s_lshl_b32 s60, s14, 8
	s_lshl_b32 s33, s8, 8
	s_add_u32 s12, s12, 0x8000000
	s_addc_u32 s13, s13, 0
	s_add_u32 s14, s6, 0x2400000
	s_addc_u32 s15, s7, 0
	s_lshl_b32 s6, s16, 5
	s_mov_b64 s[16:17], 0x80
	s_and_b32 s20, s6, 0x60
	s_add_i32 m0, s55, 0x18000
	v_lshl_add_u64 v[6:7], v[6:7], 0, s[16:17]
	s_lshl_b32 s8, s19, 13
	s_lshl_b32 s21, s20, 7
	s_waitcnt vmcnt(2)
	s_barrier
	global_load_lds_dwordx4 v[6:7], off
	v_lshl_add_u64 v[4:5], v[4:5], 0, s[16:17]
	s_add_i32 m0, s55, 0x1a000
	s_add_i32 s59, s55, 0x8000
	s_add_i32 s61, s55, 0xa000
	global_load_lds_dwordx4 v[4:5], off
	v_lshl_add_u64 v[0:1], v[0:1], 0, s[16:17]
	s_mov_b32 m0, s59
	s_add_u32 s6, s2, 0x40080
	global_load_lds_dwordx4 v[0:1], off
	v_lshl_add_u64 v[0:1], v[2:3], 0, s[16:17]
	s_mov_b32 m0, s61
	s_addc_u32 s7, s3, 0
	global_load_lds_dwordx4 v[0:1], off
	s_add_i32 m0, s55, 0x1c000
	v_lshl_add_u64 v[0:1], s[6:7], 0, v[132:133]
	global_load_lds_dwordx4 v[0:1], off
	v_lshl_add_u64 v[0:1], s[6:7], 0, v[128:129]
	s_add_i32 m0, s55, 0x1e000
	v_lshlrev_b32_e32 v4, 2, v10
	global_load_lds_dwordx4 v[0:1], off
	v_lshrrev_b32_e32 v0, 1, v10
	v_and_b32_e32 v1, 15, v10
	v_and_b32_e32 v0, 24, v0
	v_lshl_or_b32 v146, s19, 6, v1
	v_lshlrev_b32_e32 v2, 1, v0
	v_lshl_or_b32 v1, v1, 6, v2
	v_lshlrev_b32_e32 v2, 2, v146
	v_and_b32_e32 v3, 32, v2
	v_and_b32_e32 v4, 32, v4
	v_bitop3_b32 v3, v1, s8, v3 bitop3:0xde
	v_bitop3_b32 v147, v1, s21, v4 bitop3:0xde
	v_lshlrev_b32_e32 v1, 14, v8
	v_and_b32_e32 v1, 0xffff8000, v1
	v_add_u32_e32 v148, s54, v2
	v_lshl_add_u32 v1, v9, 11, v1
	v_and_b32_e32 v2, 1, v8
	v_lshl_or_b32 v1, v2, 6, v1
	v_lshl_add_u32 v138, v11, 1, v1
	v_lshlrev_b32_e32 v1, 14, v13
	v_and_b32_e32 v1, 0xffff8000, v1
	s_waitcnt vmcnt(6)
	s_cmpk_lt_u32 s18, 0x100
	v_or_b32_e32 v149, 16, v146
	v_or_b32_e32 v151, 32, v146
	v_or_b32_e32 v153, 48, v146
	v_add_u32_e32 v156, 0x80, v146
	v_add_u32_e32 v158, 0x90, v146
	v_add_u32_e32 v160, 0xa0, v146
	v_add_u32_e32 v162, 0xb0, v146
	v_lshl_add_u32 v1, v12, 11, v1
	v_and_b32_e32 v2, 1, v13
	s_cselect_b64 s[18:19], -1, 0
	v_lshl_add_u32 v150, v149, 2, s54
	v_lshl_add_u32 v152, v151, 2, s54
	v_lshl_add_u32 v155, v153, 2, s54
	v_lshl_add_u32 v157, v156, 2, s54
	v_lshl_add_u32 v159, v158, 2, s54
	v_lshl_add_u32 v161, v160, 2, s54
	v_lshl_add_u32 v163, v162, 2, s54
	v_lshl_or_b32 v1, v2, 6, v1
	s_add_i32 s54, 0, 0x10000
	s_add_i32 s62, 0, 0x14000
	v_mov_b32_e32 v139, v137
	v_lshl_add_u32 v140, v14, 1, v1
	v_mov_b32_e32 v141, v137
	v_mov_b64_e32 v[142:143], 0xb00
	v_mov_b64_e32 v[144:145], 0xaff
	v_add_u32_e32 v164, s54, v147
	v_add_u32_e32 v165, s62, v147
	v_add_u32_e32 v166, 0, v3
	v_mov_b32_e32 v167, 0x358637bd
	s_mov_b32 s63, 0xf800000
	v_mov_b32_e32 v168, 0x260
	s_movk_i32 s64, 0x1600
	s_lshl_b32 s8, s20, 1
	v_lshlrev_b32_e32 v136, 1, v0
	s_mov_b32 s65, s9
	s_barrier
	v_mov_b64_e32 v[248:249], s[12:13]
	v_add_u32_e32 v252, s60, v160
	s_nop 0
	v_mad_i64_i32 v[252:253], s[100:101], v252, s64, v[248:249]
	s_nop 4
	s_ashr_i32 s100, s33, 1
	s_ashr_i32 s101, s100, 31
	s_lshl_b64 s[100:101], s[100:101], 1
	v_lshl_add_u64 v[252:253], v[252:253], 0, s[100:101]
	v_lshl_add_u64 v[252:253], v[252:253], 0, s[8:9]
	v_lshl_add_u64 v[252:253], v[252:253], 0, v[136:137]
	s_branch .LBB0_822

; __device__ __forceinline__ int xcd_remap(int L, int nwg) { const int q = nwg / NXCD, r = nwg % NXCD, xcd = L % NXCD, off = L / NXCD; return (xcd < r ? xcd * (q + 1) : r * (q + 1) + (xcd - r) * q) + off; }
; #define PG8_STAGE(bufoff, gbase, voff) do { _Pragma("unroll") for (int _i = 0; _i < 2; ++_i) \
;         __builtin_amdgcn_global_load_lds((const unsigned*)((const char*)(gbase) + (voff)[_i]), (PG8_LAS unsigned*)(lds + (bufoff) + ldsw + _i * 8192), 16, 0, 0); } while (0)
; #define PG8_LDA(dst, b, h) do { _Pragma("unroll") for (int m = 0; m < 4; ++m) _Pragma("unroll") for (int k = 0; k < 2; ++k) dst[m][k] = *(const PG8_LAS bf16x8*)(lds + PG8_SA(b, h) + aoff + m * 2048 + k * 1024); } while (0)
; #define PG8_WAIT_V(n) asm volatile("s_waitcnt vmcnt(" #n ")" ::: "memory")
;     __device__ bool next(int i, Unit& u) const {
;         const long L = (long)i * G + c; if (L >= nwg) return false;
;         const int wgid = xcd_remap((int)L, nwg);
;         const int nig = WGM * nN, gid = wgid / nig, fm = gid * WGM, gsz = (nM - fm) < WGM ? (nM - fm) : WGM;
;         int pm = fm + ((wgid % nig) % gsz); const int pn = (wgid % nig) / gsz;
;         if (perm) { const int x = pm >> 4, j = pm & 15; pm = (j < 8) ? 8 * x + j : 64 + 8 * x + (j - 8); } u.aoff = (size_t)pm * atile; u.boff = (size_t)pn * btile + (size_t)(pm >> 3) * bbatch; u.r0 = pm * BM; u.c0 = pn * BM; u.sel = 0; return true;
; template <class Epi, class Sched>
; __device__ __forceinline__ void gemm_phase(PG8_LAS unsigned char* lds, PG8_LAS unsigned char* xl, const Gemm g, const Sched& S, const Epi& E) {
;     ...
;         const bool has_next = S.next(ui + 1, nxt);
;         const char* nA = has_next ? (const char*)g.A + nxt.aoff : cA; const char* nB = has_next ? (const char*)g.Bt + nxt.boff : cB;
; #pragma unroll 1
;         for (int t = 0; t < nt; t += 2) {
;             const bool last = (t == nt - 2);
;             const char* a1 = cA + (size_t)(t + 1) * kstep;
;             const char* a2 = last ? nA : cA + (size_t)(t + 2) * kstep; const char* b2 = last ? nB : cB + (size_t)(t + 2) * kstep;
;             const char* a3 = a2 + kstep; const char* b3 = b2 + kstep;
;             PG8_LDB(B0, 0, 0); PG8_LDB(B1, 0, 1); PG8_SCHED; PG8_LDA(At, 0, 0); PG8_STAGE(PG8_SA(1, 1), a1 + hsA, voffA);
;             PG8_WAIT_V(8); PG8_WAIT_L(0); PG8_BAR; PG8_MMA(0, 0, At, B0); PG8_MMA(0, 1, At, B1); PG8_BAR; PG8_SCHED;
.LBB0_822:
	s_add_i32 s65, s65, 1
	s_mul_i32 s6, s65, s71
	s_mul_hi_u32 s7, s65, s40
	s_add_i32 s7, s7, s6
	s_mul_i32 s6, s65, s40
	s_add_u32 s26, s6, s36
	s_addc_u32 s27, s7, s52
	v_cmp_gt_i64_e32 vcc, s[26:27], v[144:145]
	v_cmp_lt_i64_e64 s[6:7], s[26:27], v[142:143]
	s_cbranch_vccnz .LBB0_824
	s_ashr_i32 s20, s26, 31
	s_lshr_b32 s20, s20, 29
	s_add_i32 s20, s26, s20
	s_ashr_i32 s21, s20, 3
	s_and_b32 s20, s20, -8
	s_sub_i32 s20, s26, s20
	s_cmp_lt_i32 s20, 0
	s_cselect_b32 s22, s53, 0x160
	s_mul_i32 s20, s20, s22
	s_add_i32 s20, s20, s21
	s_mul_hi_i32 s21, s20, 0x2e8ba2e9
	s_lshr_b32 s22, s21, 31
	s_ashr_i32 s21, s21, 5
	s_add_i32 s21, s21, s22
	s_lshl_b32 s22, s21, 3
	s_sub_i32 s23, 0x80, s22
	s_min_i32 s23, s23, 8
	s_abs_i32 s26, s23
	v_cvt_f32_u32_e32 v254, s26
	s_sub_i32 s28, 0, s26
	s_mulk_i32 s21, 0xb0
	s_sub_i32 s20, s20, s21
	v_rcp_iflag_f32_e32 v254, v254
	s_abs_i32 s21, s20
	s_xor_b32 s27, s20, s23
	s_ashr_i32 s27, s27, 31
	v_mul_f32_e32 v254, 0x4f7ffffe, v254
	v_cvt_u32_f32_e32 v254, v254
	s_nop 0
	v_readfirstlane_b32 s29, v254
	s_mul_i32 s28, s28, s29
	s_mul_hi_u32 s28, s29, s28
	s_add_i32 s29, s29, s28
	s_mul_hi_u32 s28, s21, s29
	s_mul_i32 s29, s28, s26
	s_sub_i32 s21, s21, s29
	s_add_i32 s34, s28, 1
	s_sub_i32 s29, s21, s26
	s_cmp_ge_u32 s21, s26
	s_cselect_b32 s28, s34, s28
	s_cselect_b32 s21, s29, s21
	s_add_i32 s29, s28, 1
	s_cmp_ge_u32 s21, s26
	s_cselect_b32 s21, s29, s28
	s_xor_b32 s21, s21, s27
	s_sub_i32 s26, s21, s27
	s_mul_i32 s21, s26, s23
	s_sub_i32 s20, s20, s21
	s_add_i32 s28, s22, s20
	s_ashr_i32 s29, s28, 31
	s_ashr_i32 s27, s26, 31
	s_lshl_b64 s[20:21], s[28:29], 19
	s_lshl_b64 s[22:23], s[26:27], 19
	s_lshl_b32 s67, s28, 8
	s_lshl_b32 s66, s26, 8
.LBB0_824:
	s_add_u32 s26, s37, s20
	s_addc_u32 s27, s42, s21
	s_and_b64 s[28:29], s[6:7], exec
	s_cselect_b32 s46, s27, s31
	s_cselect_b32 s47, s26, s30
	s_add_u32 s28, s43, s22
	s_addc_u32 s29, s50, s23
	s_and_b64 s[34:35], s[6:7], exec
	s_cselect_b32 s70, s29, s3
	s_cselect_b32 s72, s28, s2
	s_add_u32 s73, s2, 0x100
	s_addc_u32 s74, s3, 0
	s_add_u32 s2, s30, 0x40080
	s_nop 0
	s_addc_u32 s3, s31, 0
	s_mov_b32 s75, -2
	ds_read_b128 v[170:173], v164
	ds_read_b128 v[174:177], v164 offset:1024
	ds_read_b128 v[180:183], v164 offset:2048
	ds_read_b128 v[184:187], v164 offset:3072
	ds_read_b128 v[188:191], v165
	ds_read_b128 v[192:195], v165 offset:1024
	ds_read_b128 v[196:199], v165 offset:2048
	ds_read_b128 v[200:203], v165 offset:3072
	s_add_u32 s30, s2, 0xfffc0080
	s_addc_u32 s31, s3, -1
	s_cmp_eq_u32 s75, 12
	s_cselect_b32 s35, s46, s31
	s_cselect_b32 s34, s47, s30
	s_cselect_b32 s31, s70, s74
	s_cselect_b32 s30, s72, s73
	v_lshl_add_u64 v[238:239], s[2:3], 0, v[140:141]
	s_add_i32 m0, s55, 0xc000
	ds_read_b128 v[204:207], v166
	ds_read_b128 v[208:211], v166 offset:1024
	ds_read_b128 v[212:215], v166 offset:2048
	ds_read_b128 v[216:219], v166 offset:3072
	ds_read_b128 v[222:225], v166 offset:4096
	ds_read_b128 v[226:229], v166 offset:5120
	ds_read_b128 v[230:233], v166 offset:6144
	ds_read_b128 v[234:237], v166 offset:7168
	global_load_lds_dwordx4 v[238:239], off
	v_lshl_add_u64 v[238:239], s[2:3], 0, v[138:139]
	s_add_i32 m0, s55, 0xe000
	s_nop 0
	global_load_lds_dwordx4 v[238:239], off
	s_waitcnt vmcnt(8)
	s_waitcnt lgkmcnt(0)
	s_barrier
	s_setprio 1
	s_waitcnt lgkmcnt(0)
	v_mfma_f32_16x16x32_bf16 v[124:127], v[170:173], v[204:207], 0
	v_mul_f32_e32 v24, v28, v24
	v_mul_f32_e32 v25, v29, v25
	v_mul_f32_e32 v26, v30, v26
	v_mul_f32_e32 v27, v31, v27
	v_mul_f32_e32 v16, v20, v16
	v_mfma_f32_16x16x32_bf16 v[116:119], v[180:183], v[204:207], 0
	v_mul_f32_e32 v17, v21, v17
	v_mul_f32_e32 v18, v22, v18
	v_mul_f32_e32 v19, v23, v19
	v_mul_f32_e32 v248, 0xbfb8aa3b, v179
	v_mfma_f32_16x16x32_bf16 v[108:111], v[170:173], v[212:215], 0
	v_mul_f32_e32 v250, v179, v179
	v_mul_f32_e32 v28, v28, v248
	v_mul_f32_e32 v29, v29, v248
	v_mul_f32_e32 v30, v30, v248
	v_mfma_f32_16x16x32_bf16 v[100:103], v[180:183], v[212:215], 0
	v_mul_f32_e32 v31, v31, v248
	v_mul_f32_e32 v20, v20, v248
	v_mul_f32_e32 v21, v21, v248
	v_mul_f32_e32 v22, v22, v248
	v_mfma_f32_16x16x32_bf16 v[92:95], v[170:173], v[222:225], 0
	v_mul_f32_e32 v23, v23, v248
	v_exp_f32_e32 v28, v28
	v_exp_f32_e32 v29, v29
	v_exp_f32_e32 v30, v30
	v_mfma_f32_16x16x32_bf16 v[84:87], v[180:183], v[222:225], 0
	v_exp_f32_e32 v31, v31
	v_exp_f32_e32 v20, v20
	v_exp_f32_e32 v21, v21
	v_exp_f32_e32 v22, v22
	v_mfma_f32_16x16x32_bf16 v[76:79], v[170:173], v[230:233], 0
	v_exp_f32_e32 v23, v23
	v_add_f32_e32 v28, 1.0, v28
	v_add_f32_e32 v29, 1.0, v29
	v_add_f32_e32 v30, 1.0, v30
	v_mfma_f32_16x16x32_bf16 v[68:71], v[180:183], v[230:233], 0
	v_add_f32_e32 v31, 1.0, v31
	v_add_f32_e32 v20, 1.0, v20
	v_add_f32_e32 v21, 1.0, v21
	v_add_f32_e32 v22, 1.0, v22
	v_mfma_f32_16x16x32_bf16 v[124:127], v[174:177], v[208:211], v[124:127]
	v_add_f32_e32 v23, 1.0, v23
	v_rcp_f32_e32 v28, v28
	v_rcp_f32_e32 v29, v29
	v_rcp_f32_e32 v30, v30
	v_mfma_f32_16x16x32_bf16 v[116:119], v[184:187], v[208:211], v[116:119]
	v_rcp_f32_e32 v31, v31
	v_rcp_f32_e32 v20, v20
	v_rcp_f32_e32 v21, v21
	v_rcp_f32_e32 v22, v22
	v_mfma_f32_16x16x32_bf16 v[108:111], v[174:177], v[216:219], v[108:111]
	v_rcp_f32_e32 v23, v23
	v_mul_f32_e32 v28, v250, v28
	v_mul_f32_e32 v29, v250, v29
	v_mul_f32_e32 v30, v250, v30
	v_mfma_f32_16x16x32_bf16 v[100:103], v[184:187], v[216:219], v[100:103]
	v_mul_f32_e32 v31, v250, v31
	v_mul_f32_e32 v20, v250, v20
	v_mul_f32_e32 v21, v250, v21
	v_mul_f32_e32 v22, v250, v22
	v_mfma_f32_16x16x32_bf16 v[92:95], v[174:177], v[226:229], v[92:95]
	v_mul_f32_e32 v23, v250, v23
	v_mul_f32_e32 v24, v24, v28
	v_mul_f32_e32 v25, v25, v29
; __device__ __forceinline__ u32x4 pack8(f32x4 v0, f32x4 v1) { u32x4 w; w.x = cvt_pk_bf16(v0[0], v0[1]); w.y = cvt_pk_bf16(v0[2], v0[3]); w.z = cvt_pk_bf16(v1[0], v1[1]); w.w = cvt_pk_bf16(v1[2], v1[3]); return w; }
; #define PG8_STAGE(bufoff, gbase, voff) do { _Pragma("unroll") for (int _i = 0; _i < 2; ++_i) \
;         __builtin_amdgcn_global_load_lds((const unsigned*)((const char*)(gbase) + (voff)[_i]), (PG8_LAS unsigned*)(lds + (bufoff) + ldsw + _i * 8192), 16, 0, 0); } while (0)
; #define PG8_LDA(dst, b, h) do { _Pragma("unroll") for (int m = 0; m < 4; ++m) _Pragma("unroll") for (int k = 0; k < 2; ++k) dst[m][k] = *(const PG8_LAS bf16x8*)(lds + PG8_SA(b, h) + aoff + m * 2048 + k * 1024); } while (0)
; #define PG8_WAIT_V(n) asm volatile("s_waitcnt vmcnt(" #n ")" ::: "memory")
; #define PG8_WAIT_L(n) asm volatile("s_waitcnt lgkmcnt(" #n ")" ::: "memory")
; #define PG8_BAR __builtin_amdgcn_s_barrier()
;     __device__ __forceinline__ void operator()(Acc& acc, const Unit& u, int wr, int wc, int fr, int fq, PG8_LAS unsigned char* xl) const {
;     ...
;             for (int m = 0; m < 4; ++m) { const int rl = ai * HALF + wr * 64 + m * 16 + fr; const int row = u.r0 + rl; const float s = S[rl], cs = -LOG2E * s, s2 = s * s;
;                 f32x4 o[2];
; #pragma unroll
;                 for (int n = 0; n < 2; ++n) { const f32x4 g = acc[ai][0][m][n], gu = acc[ai][0][m][n] * acc[ai][1][m][n]; f32x4 r;
; #pragma unroll
;                     for (int e = 0; e < 4; ++e) r[e] = gu[e] * (s2 * __builtin_amdgcn_rcpf(1.f + __builtin_amdgcn_exp2f(cs * g[e])));
;                     o[n] = r; }
;                 *(u32x4*)(H + (size_t)row * ldc + (u.c0 >> 1) + wc * 32 + 8 * fq) = pack8(o[0], o[1]); }
; template <class Epi, class Sched>
; __device__ __forceinline__ void gemm_phase(PG8_LAS unsigned char* lds, PG8_LAS unsigned char* xl, const Gemm g, const Sched& S, const Epi& E) {
;     ...
;             PG8_LDB(B0, 0, 0); PG8_LDB(B1, 0, 1); PG8_SCHED; PG8_LDA(At, 0, 0); PG8_STAGE(PG8_SA(1, 1), a1 + hsA, voffA);
;             PG8_WAIT_V(8); PG8_WAIT_L(0); PG8_BAR; PG8_MMA(0, 0, At, B0); PG8_MMA(0, 1, At, B1); PG8_BAR; PG8_SCHED;
;             PG8_LDA(At, 0, 1); PG8_STAGE(PG8_SB(0, 0), b2, voffB); PG8_STAGE(PG8_SB(0, 1), b2 + hsB, voffB); PG8_STAGE(PG8_SA(0, 0), a2, voffA);
;             PG8_WAIT_V(8); PG8_WAIT_L(0); PG8_BAR; PG8_MMA(1, 0, At, B0); PG8_MMA(1, 1, At, B1); PG8_BAR; PG8_SCHED;
	v_mul_f32_e32 v26, v26, v30
	v_mfma_f32_16x16x32_bf16 v[84:87], v[184:187], v[226:229], v[84:87]
	v_mul_f32_e32 v27, v27, v31
	v_mul_f32_e32 v16, v16, v20
	v_mul_f32_e32 v17, v17, v21
	v_mul_f32_e32 v18, v18, v22
	v_mfma_f32_16x16x32_bf16 v[76:79], v[174:177], v[234:237], v[76:79]
	v_mul_f32_e32 v19, v19, v23
	v_cvt_pk_bf16_f32 v28, v24, v25
	v_cvt_pk_bf16_f32 v29, v26, v27
	v_cvt_pk_bf16_f32 v30, v16, v17
	v_mfma_f32_16x16x32_bf16 v[68:71], v[184:187], v[234:237], v[68:71]
	v_cvt_pk_bf16_f32 v31, v18, v19
	global_store_dwordx4 v[252:253], v[28:31], off
	v_add_co_u32_e32 v252, vcc, 0x16000, v252
	s_nop 1
	s_setprio 0
	s_setprio 1
	v_mfma_f32_16x16x32_bf16 v[120:123], v[188:191], v[204:207], 0
	v_addc_co_u32_e32 v253, vcc, 0, v253, vcc
	v_mul_f32_e32 v8, v12, v8
	v_mul_f32_e32 v9, v13, v9
	v_mul_f32_e32 v10, v14, v10
	v_mfma_f32_16x16x32_bf16 v[112:115], v[196:199], v[204:207], 0
	v_mul_f32_e32 v11, v15, v11
	v_mul_f32_e32 v0, v4, v0
	v_mul_f32_e32 v1, v5, v1
	v_mul_f32_e32 v2, v6, v2
	v_mfma_f32_16x16x32_bf16 v[104:107], v[188:191], v[212:215], 0
	v_mul_f32_e32 v3, v7, v3
	v_mul_f32_e32 v248, 0xbfb8aa3b, v221
	v_mul_f32_e32 v250, v221, v221
	v_mul_f32_e32 v12, v12, v248
	v_mfma_f32_16x16x32_bf16 v[96:99], v[196:199], v[212:215], 0
	v_mul_f32_e32 v13, v13, v248
	v_mul_f32_e32 v14, v14, v248
	v_mul_f32_e32 v15, v15, v248
	v_mul_f32_e32 v4, v4, v248
	v_mfma_f32_16x16x32_bf16 v[88:91], v[188:191], v[222:225], 0
	v_mul_f32_e32 v5, v5, v248
	v_mul_f32_e32 v6, v6, v248
	v_mul_f32_e32 v7, v7, v248
	v_exp_f32_e32 v12, v12
	v_mfma_f32_16x16x32_bf16 v[80:83], v[196:199], v[222:225], 0
	v_exp_f32_e32 v13, v13
	v_exp_f32_e32 v14, v14
	v_exp_f32_e32 v15, v15
	v_exp_f32_e32 v4, v4
	v_mfma_f32_16x16x32_bf16 v[72:75], v[188:191], v[230:233], 0
	v_exp_f32_e32 v5, v5
	v_exp_f32_e32 v6, v6
	v_exp_f32_e32 v7, v7
	v_add_f32_e32 v12, 1.0, v12
	v_mfma_f32_16x16x32_bf16 v[64:67], v[196:199], v[230:233], 0
	v_add_f32_e32 v13, 1.0, v13
	v_add_f32_e32 v14, 1.0, v14
	v_add_f32_e32 v15, 1.0, v15
	v_add_f32_e32 v4, 1.0, v4
	v_mfma_f32_16x16x32_bf16 v[120:123], v[192:195], v[208:211], v[120:123]
	v_add_f32_e32 v5, 1.0, v5
	v_add_f32_e32 v6, 1.0, v6
	v_add_f32_e32 v7, 1.0, v7
	v_rcp_f32_e32 v12, v12
	v_mfma_f32_16x16x32_bf16 v[112:115], v[200:203], v[208:211], v[112:115]
	v_rcp_f32_e32 v13, v13
	v_rcp_f32_e32 v14, v14
	v_rcp_f32_e32 v15, v15
	v_rcp_f32_e32 v4, v4
	v_mfma_f32_16x16x32_bf16 v[104:107], v[192:195], v[216:219], v[104:107]
	v_rcp_f32_e32 v5, v5
	v_rcp_f32_e32 v6, v6
	v_rcp_f32_e32 v7, v7
	v_mul_f32_e32 v12, v250, v12
	v_mfma_f32_16x16x32_bf16 v[96:99], v[200:203], v[216:219], v[96:99]
	v_mul_f32_e32 v13, v250, v13
	v_mul_f32_e32 v14, v250, v14
	v_mul_f32_e32 v15, v250, v15
	v_mul_f32_e32 v4, v250, v4
	v_mfma_f32_16x16x32_bf16 v[88:91], v[192:195], v[226:229], v[88:91]
	v_mul_f32_e32 v5, v250, v5
	v_mul_f32_e32 v6, v250, v6
	v_mul_f32_e32 v7, v250, v7
	v_mul_f32_e32 v8, v8, v12
	v_mfma_f32_16x16x32_bf16 v[80:83], v[200:203], v[226:229], v[80:83]
	v_mul_f32_e32 v9, v9, v13
	v_mul_f32_e32 v10, v10, v14
	v_mul_f32_e32 v11, v11, v15
	v_mul_f32_e32 v0, v0, v4
	v_mfma_f32_16x16x32_bf16 v[72:75], v[192:195], v[234:237], v[72:75]
	v_mul_f32_e32 v1, v1, v5
	v_mul_f32_e32 v2, v2, v6
	v_mul_f32_e32 v3, v3, v7
	v_cvt_pk_bf16_f32 v12, v8, v9
	v_mfma_f32_16x16x32_bf16 v[64:67], v[200:203], v[234:237], v[64:67]
	v_cvt_pk_bf16_f32 v13, v10, v11
	v_cvt_pk_bf16_f32 v14, v0, v1
	v_cvt_pk_bf16_f32 v15, v2, v3
	global_store_dwordx4 v[252:253], v[12:15], off
	s_setprio 0
	s_barrier
	s_add_i32 s68, s54, s51
	v_lshl_add_u64 v[238:239], s[30:31], 0, v[132:133]
	s_mov_b32 m0, s68
	ds_read_b128 v[204:207], v166 offset:16384
	ds_read_b128 v[208:211], v166 offset:17408
	ds_read_b128 v[212:215], v166 offset:18432
	ds_read_b128 v[216:219], v166 offset:19456
	ds_read_b128 v[222:225], v166 offset:20480
	ds_read_b128 v[226:229], v166 offset:21504
	ds_read_b128 v[230:233], v166 offset:22528
	ds_read_b128 v[234:237], v166 offset:23552
	global_load_lds_dwordx4 v[238:239], off
	s_add_i32 m0, s68, 0x2000
	s_add_u32 s76, s30, 0x40000
	v_lshl_add_u64 v[240:241], s[30:31], 0, v[128:129]
	s_addc_u32 s77, s31, 0
	s_add_i32 s68, s62, s51
	global_load_lds_dwordx4 v[240:241], off
	v_lshl_add_u64 v[242:243], s[76:77], 0, v[132:133]
	s_mov_b32 m0, s68
	v_lshl_add_u64 v[244:245], s[34:35], 0, v[130:131]
	global_load_lds_dwordx4 v[242:243], off
	v_lshl_add_u64 v[242:243], s[76:77], 0, v[128:129]
	s_add_i32 m0, s68, 0x2000
	s_nop 0
	global_load_lds_dwordx4 v[242:243], off
	v_lshl_add_u64 v[242:243], s[34:35], 0, v[134:135]
	s_mov_b32 m0, s55
	s_nop 0
	global_load_lds_dwordx4 v[242:243], off
	s_mov_b32 m0, s56
	s_nop 0
	global_load_lds_dwordx4 v[244:245], off
	s_waitcnt vmcnt(10)
	s_waitcnt lgkmcnt(0)
	s_barrier
; #define PG8_STAGE(bufoff, gbase, voff) do { _Pragma("unroll") for (int _i = 0; _i < 2; ++_i) \
;         __builtin_amdgcn_global_load_lds((const unsigned*)((const char*)(gbase) + (voff)[_i]), (PG8_LAS unsigned*)(lds + (bufoff) + ldsw + _i * 8192), 16, 0, 0); } while (0)
; #define PG8_LDA(dst, b, h) do { _Pragma("unroll") for (int m = 0; m < 4; ++m) _Pragma("unroll") for (int k = 0; k < 2; ++k) dst[m][k] = *(const PG8_LAS bf16x8*)(lds + PG8_SA(b, h) + aoff + m * 2048 + k * 1024); } while (0)
; #define PG8_LDB(dst, b, h) do { _Pragma("unroll") for (int n = 0; n < 2; ++n) _Pragma("unroll") for (int k = 0; k < 2; ++k) dst[n][k] = *(const PG8_LAS bf16x8*)(lds + PG8_SB(b, h) + boff + n * 2048 + k * 1024); } while (0)
; #define PG8_MMA(ai, bj, At, Bt) do { __builtin_amdgcn_s_setprio(1); _Pragma("unroll") for (int m = 0; m < 4; ++m) _Pragma("unroll") for (int n = 0; n < 2; ++n) _Pragma("unroll") for (int k = 0; k < 2; ++k) \
;         acc[ai][bj][m][n] = __builtin_amdgcn_mfma_f32_16x16x32_bf16(Bt[n][k], At[m][k], acc[ai][bj][m][n], 0, 0, 0); __builtin_amdgcn_s_setprio(0); } while (0)
; #define PG8_WAIT_V(n) asm volatile("s_waitcnt vmcnt(" #n ")" ::: "memory")
; #define PG8_WAIT_L(n) asm volatile("s_waitcnt lgkmcnt(" #n ")" ::: "memory")
; #define PG8_BAR __builtin_amdgcn_s_barrier()
; #define PG8_SCHED __builtin_amdgcn_sched_barrier(0)
; template <class Epi, class Sched>
; __device__ __forceinline__ void gemm_phase(PG8_LAS unsigned char* lds, PG8_LAS unsigned char* xl, const Gemm g, const Sched& S, const Epi& E) {
;     ...
;             PG8_WAIT_V(8); PG8_WAIT_L(0); PG8_BAR; PG8_MMA(1, 0, At, B0); PG8_MMA(1, 1, At, B1); PG8_BAR; PG8_SCHED;
;             PG8_LDB(B0, 1, 0); PG8_LDB(B1, 1, 1); PG8_SCHED; PG8_LDA(At, 1, 0); PG8_STAGE(PG8_SA(0, 1), a2 + hsA, voffA);
;             PG8_WAIT_V(8); PG8_WAIT_L(0); PG8_BAR; PG8_MMA(0, 0, At, B0); PG8_MMA(0, 1, At, B1); PG8_BAR; PG8_SCHED;
	s_setprio 1
	s_waitcnt lgkmcnt(0)
	v_mfma_f32_16x16x32_bf16 v[60:63], v[170:173], v[204:207], 0
	v_mfma_f32_16x16x32_bf16 v[52:55], v[180:183], v[204:207], 0
	v_mfma_f32_16x16x32_bf16 v[44:47], v[170:173], v[212:215], 0
	v_mfma_f32_16x16x32_bf16 v[36:39], v[180:183], v[212:215], 0
	v_mfma_f32_16x16x32_bf16 v[28:31], v[170:173], v[222:225], 0
	v_mfma_f32_16x16x32_bf16 v[20:23], v[180:183], v[222:225], 0
	v_mfma_f32_16x16x32_bf16 v[12:15], v[170:173], v[230:233], 0
	v_mfma_f32_16x16x32_bf16 v[4:7], v[180:183], v[230:233], 0
	v_mfma_f32_16x16x32_bf16 v[60:63], v[174:177], v[208:211], v[60:63]
	v_mfma_f32_16x16x32_bf16 v[52:55], v[184:187], v[208:211], v[52:55]
	v_mfma_f32_16x16x32_bf16 v[44:47], v[174:177], v[216:219], v[44:47]
	v_mfma_f32_16x16x32_bf16 v[36:39], v[184:187], v[216:219], v[36:39]
	v_mfma_f32_16x16x32_bf16 v[28:31], v[174:177], v[226:229], v[28:31]
	v_mfma_f32_16x16x32_bf16 v[20:23], v[184:187], v[226:229], v[20:23]
	v_mfma_f32_16x16x32_bf16 v[12:15], v[174:177], v[234:237], v[12:15]
	v_mfma_f32_16x16x32_bf16 v[4:7], v[184:187], v[234:237], v[4:7]
	s_setprio 0
	s_setprio 1
	v_mfma_f32_16x16x32_bf16 v[56:59], v[188:191], v[204:207], 0
	v_mfma_f32_16x16x32_bf16 v[48:51], v[196:199], v[204:207], 0
	v_mfma_f32_16x16x32_bf16 v[40:43], v[188:191], v[212:215], 0
	v_mfma_f32_16x16x32_bf16 v[32:35], v[196:199], v[212:215], 0
	v_mfma_f32_16x16x32_bf16 v[24:27], v[188:191], v[222:225], 0
	v_mfma_f32_16x16x32_bf16 v[16:19], v[196:199], v[222:225], 0
	v_mfma_f32_16x16x32_bf16 v[8:11], v[188:191], v[230:233], 0
	v_mfma_f32_16x16x32_bf16 v[0:3], v[196:199], v[230:233], 0
	v_mfma_f32_16x16x32_bf16 v[56:59], v[192:195], v[208:211], v[56:59]
	v_mfma_f32_16x16x32_bf16 v[48:51], v[200:203], v[208:211], v[48:51]
	v_mfma_f32_16x16x32_bf16 v[40:43], v[192:195], v[216:219], v[40:43]
	v_mfma_f32_16x16x32_bf16 v[32:35], v[200:203], v[216:219], v[32:35]
	v_mfma_f32_16x16x32_bf16 v[24:27], v[192:195], v[226:229], v[24:27]
	v_mfma_f32_16x16x32_bf16 v[16:19], v[200:203], v[226:229], v[16:19]
	v_mfma_f32_16x16x32_bf16 v[8:11], v[192:195], v[234:237], v[8:11]
	v_mfma_f32_16x16x32_bf16 v[0:3], v[200:203], v[234:237], v[0:3]
	s_setprio 0
	s_barrier
	s_add_i32 s68, 0, 0x18000
	v_add_u32_e32 v169, s68, v147
	s_add_i32 s76, 0, 0x1c000
	ds_read_b128 v[170:173], v169
	ds_read_b128 v[174:177], v169 offset:1024
	ds_read_b128 v[180:183], v169 offset:2048
	ds_read_b128 v[184:187], v169 offset:3072
	v_add_u32_e32 v169, s76, v147
	ds_read_b128 v[188:191], v169
	ds_read_b128 v[192:195], v169 offset:1024
	ds_read_b128 v[196:199], v169 offset:2048
	ds_read_b128 v[200:203], v169 offset:3072
	s_add_u32 s34, s34, 0x40000
	s_addc_u32 s35, s35, 0
	s_mov_b32 m0, s57
	v_lshl_add_u64 v[246:247], s[34:35], 0, v[134:135]
	ds_read_b128 v[204:207], v166 offset:32768
	ds_read_b128 v[208:211], v166 offset:33792
	ds_read_b128 v[212:215], v166 offset:34816
	ds_read_b128 v[216:219], v166 offset:35840
	ds_read_b128 v[222:225], v166 offset:36864
	ds_read_b128 v[226:229], v166 offset:37888
	ds_read_b128 v[230:233], v166 offset:38912
	ds_read_b128 v[234:237], v166 offset:39936
	global_load_lds_dwordx4 v[246:247], off
	v_lshl_add_u64 v[246:247], s[34:35], 0, v[130:131]
	s_mov_b32 m0, s58
	s_nop 0
	global_load_lds_dwordx4 v[246:247], off
	s_waitcnt vmcnt(10)
	s_waitcnt lgkmcnt(0)
	s_barrier
	s_setprio 1
	s_waitcnt lgkmcnt(0)
	v_mfma_f32_16x16x32_bf16 v[124:127], v[170:173], v[204:207], v[124:127]
	v_mfma_f32_16x16x32_bf16 v[116:119], v[180:183], v[204:207], v[116:119]
	v_mfma_f32_16x16x32_bf16 v[108:111], v[170:173], v[212:215], v[108:111]
	v_mfma_f32_16x16x32_bf16 v[100:103], v[180:183], v[212:215], v[100:103]
	v_mfma_f32_16x16x32_bf16 v[92:95], v[170:173], v[222:225], v[92:95]
	v_mfma_f32_16x16x32_bf16 v[84:87], v[180:183], v[222:225], v[84:87]
	v_mfma_f32_16x16x32_bf16 v[76:79], v[170:173], v[230:233], v[76:79]
	v_mfma_f32_16x16x32_bf16 v[68:71], v[180:183], v[230:233], v[68:71]
	v_mfma_f32_16x16x32_bf16 v[124:127], v[174:177], v[208:211], v[124:127]
	v_mfma_f32_16x16x32_bf16 v[116:119], v[184:187], v[208:211], v[116:119]
	v_mfma_f32_16x16x32_bf16 v[108:111], v[174:177], v[216:219], v[108:111]
	v_mfma_f32_16x16x32_bf16 v[100:103], v[184:187], v[216:219], v[100:103]
	v_mfma_f32_16x16x32_bf16 v[92:95], v[174:177], v[226:229], v[92:95]
	v_mfma_f32_16x16x32_bf16 v[84:87], v[184:187], v[226:229], v[84:87]
	v_mfma_f32_16x16x32_bf16 v[76:79], v[174:177], v[234:237], v[76:79]
	v_mfma_f32_16x16x32_bf16 v[68:71], v[184:187], v[234:237], v[68:71]
	s_setprio 0
	s_setprio 1
	v_mfma_f32_16x16x32_bf16 v[120:123], v[188:191], v[204:207], v[120:123]
	v_mfma_f32_16x16x32_bf16 v[112:115], v[196:199], v[204:207], v[112:115]
	v_mfma_f32_16x16x32_bf16 v[104:107], v[188:191], v[212:215], v[104:107]
	v_mfma_f32_16x16x32_bf16 v[96:99], v[196:199], v[212:215], v[96:99]
	v_mfma_f32_16x16x32_bf16 v[88:91], v[188:191], v[222:225], v[88:91]
	v_mfma_f32_16x16x32_bf16 v[80:83], v[196:199], v[222:225], v[80:83]
	v_mfma_f32_16x16x32_bf16 v[72:75], v[188:191], v[230:233], v[72:75]
	v_mfma_f32_16x16x32_bf16 v[64:67], v[196:199], v[230:233], v[64:67]
	v_mfma_f32_16x16x32_bf16 v[120:123], v[192:195], v[208:211], v[120:123]
	v_mfma_f32_16x16x32_bf16 v[112:115], v[200:203], v[208:211], v[112:115]
	v_mfma_f32_16x16x32_bf16 v[104:107], v[192:195], v[216:219], v[104:107]
	v_mfma_f32_16x16x32_bf16 v[96:99], v[200:203], v[216:219], v[96:99]
	v_mfma_f32_16x16x32_bf16 v[88:91], v[192:195], v[226:229], v[88:91]
	v_mfma_f32_16x16x32_bf16 v[80:83], v[200:203], v[226:229], v[80:83]
	v_mfma_f32_16x16x32_bf16 v[72:75], v[192:195], v[234:237], v[72:75]
	v_mfma_f32_16x16x32_bf16 v[64:67], v[200:203], v[234:237], v[64:67]
	s_setprio 0
	s_barrier
; #define PG8_STAGE(bufoff, gbase, voff) do { _Pragma("unroll") for (int _i = 0; _i < 2; ++_i) \
;         __builtin_amdgcn_global_load_lds((const unsigned*)((const char*)(gbase) + (voff)[_i]), (PG8_LAS unsigned*)(lds + (bufoff) + ldsw + _i * 8192), 16, 0, 0); } while (0)
; #define PG8_LDA(dst, b, h) do { _Pragma("unroll") for (int m = 0; m < 4; ++m) _Pragma("unroll") for (int k = 0; k < 2; ++k) dst[m][k] = *(const PG8_LAS bf16x8*)(lds + PG8_SA(b, h) + aoff + m * 2048 + k * 1024); } while (0)
; #define PG8_MMA(ai, bj, At, Bt) do { __builtin_amdgcn_s_setprio(1); _Pragma("unroll") for (int m = 0; m < 4; ++m) _Pragma("unroll") for (int n = 0; n < 2; ++n) _Pragma("unroll") for (int k = 0; k < 2; ++k) \
;         acc[ai][bj][m][n] = __builtin_amdgcn_mfma_f32_16x16x32_bf16(Bt[n][k], At[m][k], acc[ai][bj][m][n], 0, 0, 0); __builtin_amdgcn_s_setprio(0); } while (0)
; #define PG8_WAIT_V(n) asm volatile("s_waitcnt vmcnt(" #n ")" ::: "memory")
; #define PG8_WAIT_L(n) asm volatile("s_waitcnt lgkmcnt(" #n ")" ::: "memory")
; #define PG8_BAR __builtin_amdgcn_s_barrier()
; #define PG8_SCHED __builtin_amdgcn_sched_barrier(0)
; template <class Epi, class Sched>
; __device__ __forceinline__ void gemm_phase(PG8_LAS unsigned char* lds, PG8_LAS unsigned char* xl, const Gemm g, const Sched& S, const Epi& E) {
;     ...
;             PG8_LDA(At, 1, 1); PG8_STAGE(PG8_SB(1, 0), b3, voffB); PG8_STAGE(PG8_SB(1, 1), b3 + hsB, voffB); PG8_STAGE(PG8_SA(1, 0), a3, voffA);
;             PG8_WAIT_V(8); PG8_WAIT_L(0); PG8_BAR; PG8_MMA(1, 0, At, B0); PG8_MMA(1, 1, At, B1); PG8_BAR; PG8_SCHED;
;         }
	s_add_i32 s34, s68, s51
	v_lshl_add_u64 v[238:239], v[238:239], 0, s[16:17]
	s_mov_b32 m0, s34
	ds_read_b128 v[204:207], v166 offset:49152
	ds_read_b128 v[208:211], v166 offset:50176
	ds_read_b128 v[212:215], v166 offset:51200
	ds_read_b128 v[216:219], v166 offset:52224
	ds_read_b128 v[222:225], v166 offset:53248
	ds_read_b128 v[226:229], v166 offset:54272
	ds_read_b128 v[230:233], v166 offset:55296
	ds_read_b128 v[234:237], v166 offset:56320
	global_load_lds_dwordx4 v[238:239], off
	s_add_i32 m0, s34, 0x2000
	s_add_u32 s30, s30, 0x40080
	v_lshl_add_u64 v[238:239], v[240:241], 0, s[16:17]
	s_addc_u32 s31, s31, 0
	s_add_i32 s34, s76, s51
	global_load_lds_dwordx4 v[238:239], off
	v_lshl_add_u64 v[238:239], s[30:31], 0, v[132:133]
	s_mov_b32 m0, s34
	s_nop 0
	global_load_lds_dwordx4 v[238:239], off
	v_lshl_add_u64 v[238:239], s[30:31], 0, v[128:129]
	s_add_i32 m0, s34, 0x2000
	s_nop 0
	global_load_lds_dwordx4 v[238:239], off
	v_lshl_add_u64 v[238:239], v[242:243], 0, s[16:17]
	s_mov_b32 m0, s59
	s_nop 0
	global_load_lds_dwordx4 v[238:239], off
	v_lshl_add_u64 v[238:239], v[244:245], 0, s[16:17]
	s_mov_b32 m0, s61
	s_nop 0
	global_load_lds_dwordx4 v[238:239], off
	s_waitcnt vmcnt(8)
	s_waitcnt lgkmcnt(0)
	s_barrier
	s_setprio 1
	s_waitcnt lgkmcnt(0)
	v_mfma_f32_16x16x32_bf16 v[60:63], v[170:173], v[204:207], v[60:63]
	v_mfma_f32_16x16x32_bf16 v[52:55], v[180:183], v[204:207], v[52:55]
	v_mfma_f32_16x16x32_bf16 v[44:47], v[170:173], v[212:215], v[44:47]
	v_mfma_f32_16x16x32_bf16 v[36:39], v[180:183], v[212:215], v[36:39]
	v_mfma_f32_16x16x32_bf16 v[28:31], v[170:173], v[222:225], v[28:31]
	v_mfma_f32_16x16x32_bf16 v[20:23], v[180:183], v[222:225], v[20:23]
	v_mfma_f32_16x16x32_bf16 v[12:15], v[170:173], v[230:233], v[12:15]
	v_mfma_f32_16x16x32_bf16 v[4:7], v[180:183], v[230:233], v[4:7]
	v_mfma_f32_16x16x32_bf16 v[60:63], v[174:177], v[208:211], v[60:63]
	v_mfma_f32_16x16x32_bf16 v[52:55], v[184:187], v[208:211], v[52:55]
	v_mfma_f32_16x16x32_bf16 v[44:47], v[174:177], v[216:219], v[44:47]
	v_mfma_f32_16x16x32_bf16 v[36:39], v[184:187], v[216:219], v[36:39]
	v_mfma_f32_16x16x32_bf16 v[28:31], v[174:177], v[226:229], v[28:31]
	v_mfma_f32_16x16x32_bf16 v[20:23], v[184:187], v[226:229], v[20:23]
	v_mfma_f32_16x16x32_bf16 v[12:15], v[174:177], v[234:237], v[12:15]
	v_mfma_f32_16x16x32_bf16 v[4:7], v[184:187], v[234:237], v[4:7]
	s_setprio 0
	s_setprio 1
	v_mfma_f32_16x16x32_bf16 v[56:59], v[188:191], v[204:207], v[56:59]
	v_mfma_f32_16x16x32_bf16 v[48:51], v[196:199], v[204:207], v[48:51]
	v_mfma_f32_16x16x32_bf16 v[40:43], v[188:191], v[212:215], v[40:43]
	v_mfma_f32_16x16x32_bf16 v[32:35], v[196:199], v[212:215], v[32:35]
	v_mfma_f32_16x16x32_bf16 v[24:27], v[188:191], v[222:225], v[24:27]
	v_mfma_f32_16x16x32_bf16 v[16:19], v[196:199], v[222:225], v[16:19]
	v_mfma_f32_16x16x32_bf16 v[8:11], v[188:191], v[230:233], v[8:11]
	v_mfma_f32_16x16x32_bf16 v[0:3], v[196:199], v[230:233], v[0:3]
	v_mfma_f32_16x16x32_bf16 v[56:59], v[192:195], v[208:211], v[56:59]
	v_mfma_f32_16x16x32_bf16 v[48:51], v[200:203], v[208:211], v[48:51]
	v_mfma_f32_16x16x32_bf16 v[40:43], v[192:195], v[216:219], v[40:43]
	v_mfma_f32_16x16x32_bf16 v[32:35], v[200:203], v[216:219], v[32:35]
	v_mfma_f32_16x16x32_bf16 v[24:27], v[192:195], v[226:229], v[24:27]
	v_mfma_f32_16x16x32_bf16 v[16:19], v[200:203], v[226:229], v[16:19]
	v_mfma_f32_16x16x32_bf16 v[8:11], v[192:195], v[234:237], v[8:11]
	v_mfma_f32_16x16x32_bf16 v[0:3], v[200:203], v[234:237], v[0:3]
	s_setprio 0
	s_barrier
	s_add_i32 s75, s75, 2
	s_add_u32 s73, s73, 0x100
	s_addc_u32 s74, s74, 0
	s_add_u32 s2, s2, 0x100
	s_addc_u32 s3, s3, 0
	s_cmp_gt_u32 s75, 13
	s_cbranch_scc1 .Lpeel_after_P8

; #define PG8_LAS __attribute__((address_space(3)))
; __device__ __forceinline__ u32x4 pack8(f32x4 v0, f32x4 v1) { u32x4 w; w.x = cvt_pk_bf16(v0[0], v0[1]); w.y = cvt_pk_bf16(v0[2], v0[3]); w.z = cvt_pk_bf16(v1[0], v1[1]); w.w = cvt_pk_bf16(v1[2], v1[3]); return w; }
;     __device__ __forceinline__ void operator()(Acc& acc, const Unit& u, int wr, int wc, int fr, int fq, PG8_LAS unsigned char* xl) const {
;         const PG8_LAS float* S = rs_table(SS, u.r0, xl);
; #pragma unroll
;         for (int ai = 0; ai < 2; ++ai)
; #pragma unroll
;             for (int m = 0; m < 4; ++m) { const int rl = ai * HALF + wr * 64 + m * 16 + fr; const int row = u.r0 + rl; const float s = S[rl], cs = -LOG2E * s, s2 = s * s;
;                 f32x4 o[2];
; #pragma unroll
;                 for (int n = 0; n < 2; ++n) { const f32x4 g = acc[ai][0][m][n], gu = acc[ai][0][m][n] * acc[ai][1][m][n]; f32x4 r;
; #pragma unroll
;                     for (int e = 0; e < 4; ++e) r[e] = gu[e] * (s2 * __builtin_amdgcn_rcpf(1.f + __builtin_amdgcn_exp2f(cs * g[e])));
;                     o[n] = r; }
;                 *(u32x4*)(H + (size_t)row * ldc + (u.c0 >> 1) + wc * 32 + 8 * fq) = pack8(o[0], o[1]); }
.Lrs8_skip:
	ds_read_b32 v184, v148
	ds_read_b32 v185, v150
	ds_read_b32 v186, v152
	ds_read_b32 v187, v155
	ds_read_b32 v188, v157
	ds_read_b32 v189, v159
	ds_read_b32 v179, v161
	ds_read_b32 v221, v163
	s_ashr_i32 s2, s33, 1
	s_ashr_i32 s3, s2, 31
	s_lshl_b64 s[2:3], s[2:3], 1
	v_mov_b64_e32 v[170:171], s[12:13]
	v_mov_b32_e32 v180, 1.0
	v_pk_mul_f32 v[120:121], v[124:125], v[120:121]
	v_pk_mul_f32 v[122:123], v[126:127], v[122:123]
	v_pk_mul_f32 v[112:113], v[116:117], v[112:113]
	v_pk_mul_f32 v[114:115], v[118:119], v[114:115]
	s_waitcnt lgkmcnt(0)
	v_mul_f32_e32 v174, 0xbfb8aa3b, v184
	v_mul_f32_e32 v176, v184, v184
	v_pk_mul_f32 v[124:125], v[124:125], v[174:175] op_sel_hi:[1,0]
	v_pk_mul_f32 v[126:127], v[126:127], v[174:175] op_sel_hi:[1,0]
	v_pk_mul_f32 v[116:117], v[116:117], v[174:175] op_sel_hi:[1,0]
	v_pk_mul_f32 v[118:119], v[118:119], v[174:175] op_sel_hi:[1,0]
	v_exp_f32_e32 v124, v124
	v_exp_f32_e32 v125, v125
	v_exp_f32_e32 v126, v126
	v_exp_f32_e32 v127, v127
	v_exp_f32_e32 v116, v116
	v_exp_f32_e32 v117, v117
	v_exp_f32_e32 v118, v118
	v_exp_f32_e32 v119, v119
	v_pk_add_f32 v[124:125], v[124:125], v[180:181] op_sel_hi:[1,0]
	v_pk_add_f32 v[126:127], v[126:127], v[180:181] op_sel_hi:[1,0]
	v_pk_add_f32 v[116:117], v[116:117], v[180:181] op_sel_hi:[1,0]
	v_pk_add_f32 v[118:119], v[118:119], v[180:181] op_sel_hi:[1,0]
	v_add_u32_e32 v172, s60, v146
	v_rcp_f32_e32 v124, v124
	v_rcp_f32_e32 v125, v125
	v_rcp_f32_e32 v126, v126
	v_rcp_f32_e32 v127, v127
	v_mad_i64_i32 v[172:173], s[30:31], v172, s64, v[170:171]
	v_rcp_f32_e32 v116, v116
	v_rcp_f32_e32 v117, v117
	v_rcp_f32_e32 v118, v118
	v_rcp_f32_e32 v119, v119
	v_lshl_add_u64 v[172:173], v[172:173], 0, s[2:3]
	v_lshl_add_u64 v[172:173], v[172:173], 0, s[8:9]
	v_lshl_add_u64 v[172:173], v[172:173], 0, v[136:137]
	v_pk_mul_f32 v[124:125], v[124:125], v[176:177] op_sel_hi:[1,0]
	v_pk_mul_f32 v[126:127], v[126:127], v[176:177] op_sel_hi:[1,0]
	v_pk_mul_f32 v[116:117], v[116:117], v[176:177] op_sel_hi:[1,0]
	v_pk_mul_f32 v[118:119], v[118:119], v[176:177] op_sel_hi:[1,0]
	v_pk_mul_f32 v[120:121], v[120:121], v[124:125]
	v_pk_mul_f32 v[122:123], v[122:123], v[126:127]
	v_pk_mul_f32 v[112:113], v[112:113], v[116:117]
	v_pk_mul_f32 v[114:115], v[114:115], v[118:119]
	v_cvt_pk_bf16_f32 v124, v120, v121
	v_cvt_pk_bf16_f32 v125, v122, v123
	v_cvt_pk_bf16_f32 v126, v112, v113
	v_cvt_pk_bf16_f32 v127, v114, v115
	flat_store_dwordx4 v[172:173], v[124:127]
	v_pk_mul_f32 v[104:105], v[108:109], v[104:105]
	v_pk_mul_f32 v[106:107], v[110:111], v[106:107]
	v_pk_mul_f32 v[96:97], v[100:101], v[96:97]
	v_pk_mul_f32 v[98:99], v[102:103], v[98:99]
	v_mul_f32_e32 v174, 0xbfb8aa3b, v185
	v_mul_f32_e32 v176, v185, v185
	v_pk_mul_f32 v[108:109], v[108:109], v[174:175] op_sel_hi:[1,0]
	v_pk_mul_f32 v[110:111], v[110:111], v[174:175] op_sel_hi:[1,0]
	v_pk_mul_f32 v[100:101], v[100:101], v[174:175] op_sel_hi:[1,0]
	v_pk_mul_f32 v[102:103], v[102:103], v[174:175] op_sel_hi:[1,0]
	v_exp_f32_e32 v108, v108
	v_exp_f32_e32 v109, v109
	v_exp_f32_e32 v110, v110
	v_exp_f32_e32 v111, v111
	v_exp_f32_e32 v100, v100
	v_exp_f32_e32 v101, v101
	v_exp_f32_e32 v102, v102
	v_exp_f32_e32 v103, v103
	v_pk_add_f32 v[108:109], v[108:109], v[180:181] op_sel_hi:[1,0]
	v_pk_add_f32 v[110:111], v[110:111], v[180:181] op_sel_hi:[1,0]
	v_pk_add_f32 v[100:101], v[100:101], v[180:181] op_sel_hi:[1,0]
	v_pk_add_f32 v[102:103], v[102:103], v[180:181] op_sel_hi:[1,0]
	v_add_co_u32_e32 v172, vcc, 0x16000, v172
	v_rcp_f32_e32 v108, v108
	v_rcp_f32_e32 v109, v109
	v_rcp_f32_e32 v110, v110
	v_rcp_f32_e32 v111, v111
	v_addc_co_u32_e32 v173, vcc, 0, v173, vcc
	v_rcp_f32_e32 v100, v100
	v_rcp_f32_e32 v101, v101
	v_rcp_f32_e32 v102, v102
	v_rcp_f32_e32 v103, v103
	v_pk_mul_f32 v[108:109], v[108:109], v[176:177] op_sel_hi:[1,0]
	v_pk_mul_f32 v[110:111], v[110:111], v[176:177] op_sel_hi:[1,0]
	v_pk_mul_f32 v[100:101], v[100:101], v[176:177] op_sel_hi:[1,0]
	v_pk_mul_f32 v[102:103], v[102:103], v[176:177] op_sel_hi:[1,0]
	v_pk_mul_f32 v[104:105], v[104:105], v[108:109]
	v_pk_mul_f32 v[106:107], v[106:107], v[110:111]
	v_pk_mul_f32 v[96:97], v[96:97], v[100:101]
	v_pk_mul_f32 v[98:99], v[98:99], v[102:103]
	v_cvt_pk_bf16_f32 v108, v104, v105
	v_cvt_pk_bf16_f32 v109, v106, v107
	v_cvt_pk_bf16_f32 v110, v96, v97
	v_cvt_pk_bf16_f32 v111, v98, v99
	flat_store_dwordx4 v[172:173], v[108:111]
	v_pk_mul_f32 v[88:89], v[92:93], v[88:89]
	v_pk_mul_f32 v[90:91], v[94:95], v[90:91]
	v_pk_mul_f32 v[80:81], v[84:85], v[80:81]
	v_pk_mul_f32 v[82:83], v[86:87], v[82:83]
	v_mul_f32_e32 v174, 0xbfb8aa3b, v186
	v_mul_f32_e32 v176, v186, v186
	v_pk_mul_f32 v[92:93], v[92:93], v[174:175] op_sel_hi:[1,0]
	v_pk_mul_f32 v[94:95], v[94:95], v[174:175] op_sel_hi:[1,0]
	v_pk_mul_f32 v[84:85], v[84:85], v[174:175] op_sel_hi:[1,0]
	v_pk_mul_f32 v[86:87], v[86:87], v[174:175] op_sel_hi:[1,0]
	v_exp_f32_e32 v92, v92
	v_exp_f32_e32 v93, v93
	v_exp_f32_e32 v94, v94
	v_exp_f32_e32 v95, v95
	v_exp_f32_e32 v84, v84
	v_exp_f32_e32 v85, v85
	v_exp_f32_e32 v86, v86
	v_exp_f32_e32 v87, v87
	v_pk_add_f32 v[92:93], v[92:93], v[180:181] op_sel_hi:[1,0]
	v_pk_add_f32 v[94:95], v[94:95], v[180:181] op_sel_hi:[1,0]
	v_pk_add_f32 v[84:85], v[84:85], v[180:181] op_sel_hi:[1,0]
	v_pk_add_f32 v[86:87], v[86:87], v[180:181] op_sel_hi:[1,0]
	v_add_co_u32_e32 v172, vcc, 0x16000, v172
	v_rcp_f32_e32 v92, v92
	v_rcp_f32_e32 v93, v93
	v_rcp_f32_e32 v94, v94
	v_rcp_f32_e32 v95, v95
	v_addc_co_u32_e32 v173, vcc, 0, v173, vcc
	v_rcp_f32_e32 v84, v84
	v_rcp_f32_e32 v85, v85
	v_rcp_f32_e32 v86, v86
	v_rcp_f32_e32 v87, v87
	v_pk_mul_f32 v[92:93], v[92:93], v[176:177] op_sel_hi:[1,0]
; __device__ __forceinline__ u32x4 pack8(f32x4 v0, f32x4 v1) { u32x4 w; w.x = cvt_pk_bf16(v0[0], v0[1]); w.y = cvt_pk_bf16(v0[2], v0[3]); w.z = cvt_pk_bf16(v1[0], v1[1]); w.w = cvt_pk_bf16(v1[2], v1[3]); return w; }
; #define PG8_BAR __builtin_amdgcn_s_barrier()
;     __device__ __forceinline__ void operator()(Acc& acc, const Unit& u, int wr, int wc, int fr, int fq, PG8_LAS unsigned char* xl) const {
;     ...
;         for (int ai = 0; ai < 2; ++ai)
; #pragma unroll
;             for (int m = 0; m < 4; ++m) { const int rl = ai * HALF + wr * 64 + m * 16 + fr; const int row = u.r0 + rl; const float s = S[rl], cs = -LOG2E * s, s2 = s * s;
;                 f32x4 o[2];
; #pragma unroll
;                 for (int n = 0; n < 2; ++n) { const f32x4 g = acc[ai][0][m][n], gu = acc[ai][0][m][n] * acc[ai][1][m][n]; f32x4 r;
; #pragma unroll
;                     for (int e = 0; e < 4; ++e) r[e] = gu[e] * (s2 * __builtin_amdgcn_rcpf(1.f + __builtin_amdgcn_exp2f(cs * g[e])));
;                     o[n] = r; }
;                 *(u32x4*)(H + (size_t)row * ldc + (u.c0 >> 1) + wc * 32 + 8 * fq) = pack8(o[0], o[1]); }
; template <class Epi, class Sched>
; __device__ __forceinline__ void gemm_phase(PG8_LAS unsigned char* lds, PG8_LAS unsigned char* xl, const Gemm g, const Sched& S, const Epi& E) {
;     ...
;         if (!has_next) break;
; #pragma unroll
;         for (int a = 0; a < 2; ++a)
; #pragma unroll
;             for (int b = 0; b < 2; ++b)
; #pragma unroll
;                 for (int m = 0; m < 4; ++m)
; #pragma unroll
;                     for (int n = 0; n < 2; ++n) acc[a][b][m][n] = (f32x4){0.f, 0.f, 0.f, 0.f};
;         cur = nxt; cA = nA; cB = nB; ++ui;
;         if (wr == 1) PG8_BAR;
	v_pk_mul_f32 v[94:95], v[94:95], v[176:177] op_sel_hi:[1,0]
	v_pk_mul_f32 v[84:85], v[84:85], v[176:177] op_sel_hi:[1,0]
	v_pk_mul_f32 v[86:87], v[86:87], v[176:177] op_sel_hi:[1,0]
	v_pk_mul_f32 v[88:89], v[88:89], v[92:93]
	v_pk_mul_f32 v[90:91], v[90:91], v[94:95]
	v_pk_mul_f32 v[80:81], v[80:81], v[84:85]
	v_pk_mul_f32 v[82:83], v[82:83], v[86:87]
	v_cvt_pk_bf16_f32 v92, v88, v89
	v_cvt_pk_bf16_f32 v93, v90, v91
	v_cvt_pk_bf16_f32 v94, v80, v81
	v_cvt_pk_bf16_f32 v95, v82, v83
	flat_store_dwordx4 v[172:173], v[92:95]
	v_pk_mul_f32 v[72:73], v[76:77], v[72:73]
	v_pk_mul_f32 v[74:75], v[78:79], v[74:75]
	v_pk_mul_f32 v[64:65], v[68:69], v[64:65]
	v_pk_mul_f32 v[66:67], v[70:71], v[66:67]
	v_mul_f32_e32 v174, 0xbfb8aa3b, v187
	v_mul_f32_e32 v176, v187, v187
	v_pk_mul_f32 v[76:77], v[76:77], v[174:175] op_sel_hi:[1,0]
	v_pk_mul_f32 v[78:79], v[78:79], v[174:175] op_sel_hi:[1,0]
	v_pk_mul_f32 v[68:69], v[68:69], v[174:175] op_sel_hi:[1,0]
	v_pk_mul_f32 v[70:71], v[70:71], v[174:175] op_sel_hi:[1,0]
	v_exp_f32_e32 v76, v76
	v_exp_f32_e32 v77, v77
	v_exp_f32_e32 v78, v78
	v_exp_f32_e32 v79, v79
	v_exp_f32_e32 v68, v68
	v_exp_f32_e32 v69, v69
	v_exp_f32_e32 v70, v70
	v_exp_f32_e32 v71, v71
	v_pk_add_f32 v[76:77], v[76:77], v[180:181] op_sel_hi:[1,0]
	v_pk_add_f32 v[78:79], v[78:79], v[180:181] op_sel_hi:[1,0]
	v_pk_add_f32 v[68:69], v[68:69], v[180:181] op_sel_hi:[1,0]
	v_pk_add_f32 v[70:71], v[70:71], v[180:181] op_sel_hi:[1,0]
	v_add_co_u32_e32 v172, vcc, 0x16000, v172
	v_rcp_f32_e32 v76, v76
	v_rcp_f32_e32 v77, v77
	v_rcp_f32_e32 v78, v78
	v_rcp_f32_e32 v79, v79
	v_addc_co_u32_e32 v173, vcc, 0, v173, vcc
	v_rcp_f32_e32 v68, v68
	v_rcp_f32_e32 v69, v69
	v_rcp_f32_e32 v70, v70
	v_rcp_f32_e32 v71, v71
	v_pk_mul_f32 v[76:77], v[76:77], v[176:177] op_sel_hi:[1,0]
	v_pk_mul_f32 v[78:79], v[78:79], v[176:177] op_sel_hi:[1,0]
	v_pk_mul_f32 v[68:69], v[68:69], v[176:177] op_sel_hi:[1,0]
	v_pk_mul_f32 v[70:71], v[70:71], v[176:177] op_sel_hi:[1,0]
	v_pk_mul_f32 v[72:73], v[72:73], v[76:77]
	v_pk_mul_f32 v[74:75], v[74:75], v[78:79]
	v_pk_mul_f32 v[64:65], v[64:65], v[68:69]
	v_pk_mul_f32 v[66:67], v[66:67], v[70:71]
	v_cvt_pk_bf16_f32 v76, v72, v73
	v_cvt_pk_bf16_f32 v77, v74, v75
	v_cvt_pk_bf16_f32 v78, v64, v65
	v_cvt_pk_bf16_f32 v79, v66, v67
	flat_store_dwordx4 v[172:173], v[76:79]
	v_pk_mul_f32 v[56:57], v[60:61], v[56:57]
	v_pk_mul_f32 v[58:59], v[62:63], v[58:59]
	v_pk_mul_f32 v[48:49], v[52:53], v[48:49]
	v_pk_mul_f32 v[50:51], v[54:55], v[50:51]
	v_mul_f32_e32 v174, 0xbfb8aa3b, v188
	v_mul_f32_e32 v176, v188, v188
	v_pk_mul_f32 v[60:61], v[60:61], v[174:175] op_sel_hi:[1,0]
	v_pk_mul_f32 v[62:63], v[62:63], v[174:175] op_sel_hi:[1,0]
	v_pk_mul_f32 v[52:53], v[52:53], v[174:175] op_sel_hi:[1,0]
	v_pk_mul_f32 v[54:55], v[54:55], v[174:175] op_sel_hi:[1,0]
	v_exp_f32_e32 v60, v60
	v_exp_f32_e32 v61, v61
	v_exp_f32_e32 v62, v62
	v_exp_f32_e32 v63, v63
	v_exp_f32_e32 v52, v52
	v_exp_f32_e32 v53, v53
	v_exp_f32_e32 v54, v54
	v_exp_f32_e32 v55, v55
	v_pk_add_f32 v[60:61], v[60:61], v[180:181] op_sel_hi:[1,0]
	v_pk_add_f32 v[62:63], v[62:63], v[180:181] op_sel_hi:[1,0]
	v_pk_add_f32 v[52:53], v[52:53], v[180:181] op_sel_hi:[1,0]
	v_pk_add_f32 v[54:55], v[54:55], v[180:181] op_sel_hi:[1,0]
	v_add_co_u32_e32 v172, vcc, 0x6e000, v172
	v_rcp_f32_e32 v60, v60
	v_rcp_f32_e32 v61, v61
	v_rcp_f32_e32 v62, v62
	v_rcp_f32_e32 v63, v63
	v_addc_co_u32_e32 v173, vcc, 0, v173, vcc
	v_rcp_f32_e32 v52, v52
	v_rcp_f32_e32 v53, v53
	v_rcp_f32_e32 v54, v54
	v_rcp_f32_e32 v55, v55
	v_pk_mul_f32 v[60:61], v[60:61], v[176:177] op_sel_hi:[1,0]
	v_pk_mul_f32 v[62:63], v[62:63], v[176:177] op_sel_hi:[1,0]
	v_pk_mul_f32 v[52:53], v[52:53], v[176:177] op_sel_hi:[1,0]
	v_pk_mul_f32 v[54:55], v[54:55], v[176:177] op_sel_hi:[1,0]
	v_pk_mul_f32 v[56:57], v[56:57], v[60:61]
	v_pk_mul_f32 v[58:59], v[58:59], v[62:63]
	v_pk_mul_f32 v[48:49], v[48:49], v[52:53]
	v_pk_mul_f32 v[50:51], v[50:51], v[54:55]
	v_cvt_pk_bf16_f32 v60, v56, v57
	v_cvt_pk_bf16_f32 v61, v58, v59
	v_cvt_pk_bf16_f32 v62, v48, v49
	v_cvt_pk_bf16_f32 v63, v50, v51
	flat_store_dwordx4 v[172:173], v[60:63]
	v_pk_mul_f32 v[40:41], v[44:45], v[40:41]
	v_pk_mul_f32 v[42:43], v[46:47], v[42:43]
	v_pk_mul_f32 v[32:33], v[36:37], v[32:33]
	v_pk_mul_f32 v[34:35], v[38:39], v[34:35]
	v_mul_f32_e32 v174, 0xbfb8aa3b, v189
	v_mul_f32_e32 v176, v189, v189
	v_pk_mul_f32 v[44:45], v[44:45], v[174:175] op_sel_hi:[1,0]
	v_pk_mul_f32 v[46:47], v[46:47], v[174:175] op_sel_hi:[1,0]
	v_pk_mul_f32 v[36:37], v[36:37], v[174:175] op_sel_hi:[1,0]
	v_pk_mul_f32 v[38:39], v[38:39], v[174:175] op_sel_hi:[1,0]
	v_exp_f32_e32 v44, v44
	v_exp_f32_e32 v45, v45
	v_exp_f32_e32 v46, v46
	v_exp_f32_e32 v47, v47
	v_exp_f32_e32 v36, v36
	v_exp_f32_e32 v37, v37
	v_exp_f32_e32 v38, v38
	v_exp_f32_e32 v39, v39
	v_pk_add_f32 v[44:45], v[44:45], v[180:181] op_sel_hi:[1,0]
	v_pk_add_f32 v[46:47], v[46:47], v[180:181] op_sel_hi:[1,0]
	v_pk_add_f32 v[36:37], v[36:37], v[180:181] op_sel_hi:[1,0]
	v_pk_add_f32 v[38:39], v[38:39], v[180:181] op_sel_hi:[1,0]
	v_add_co_u32_e32 v172, vcc, 0x16000, v172
	v_rcp_f32_e32 v44, v44
	v_rcp_f32_e32 v45, v45
	v_rcp_f32_e32 v46, v46
	v_rcp_f32_e32 v47, v47
	v_addc_co_u32_e32 v173, vcc, 0, v173, vcc
	v_rcp_f32_e32 v36, v36
	v_rcp_f32_e32 v37, v37
	v_rcp_f32_e32 v38, v38
	v_rcp_f32_e32 v39, v39
	v_add_co_u32_e32 v252, vcc, 0x16000, v172
	v_pk_mul_f32 v[44:45], v[44:45], v[176:177] op_sel_hi:[1,0]
	v_pk_mul_f32 v[46:47], v[46:47], v[176:177] op_sel_hi:[1,0]
	v_pk_mul_f32 v[36:37], v[36:37], v[176:177] op_sel_hi:[1,0]
	v_pk_mul_f32 v[38:39], v[38:39], v[176:177] op_sel_hi:[1,0]
	v_addc_co_u32_e32 v253, vcc, 0, v173, vcc
	v_pk_mul_f32 v[40:41], v[40:41], v[44:45]
	v_pk_mul_f32 v[42:43], v[42:43], v[46:47]
	v_pk_mul_f32 v[32:33], v[32:33], v[36:37]
	v_pk_mul_f32 v[34:35], v[34:35], v[38:39]
	v_cvt_pk_bf16_f32 v44, v40, v41
	v_cvt_pk_bf16_f32 v45, v42, v43
	v_cvt_pk_bf16_f32 v46, v32, v33
	v_cvt_pk_bf16_f32 v47, v34, v35
	flat_store_dwordx4 v[172:173], v[44:47]
	s_mov_b64 s[2:3], -1
	s_andn2_b64 vcc, exec, s[6:7]
	s_cbranch_vccnz .LBB0_821
	s_andn2_b64 vcc, exec, s[10:11]
	s_cbranch_vccnz .LBB0_820
	s_barrier
	s_branch .LBB0_820
; __device__ __forceinline__ u32x4 pack8(f32x4 v0, f32x4 v1) { u32x4 w; w.x = cvt_pk_bf16(v0[0], v0[1]); w.y = cvt_pk_bf16(v0[2], v0[3]); w.z = cvt_pk_bf16(v1[0], v1[1]); w.w = cvt_pk_bf16(v1[2], v1[3]); return w; }
;     __device__ __forceinline__ void operator()(Acc& acc, const Unit& u, int wr, int wc, int fr, int fq, PG8_LAS unsigned char* xl) const {
;     ...
;             for (int m = 0; m < 4; ++m) { const int rl = ai * HALF + wr * 64 + m * 16 + fr; const int row = u.r0 + rl; const float s = S[rl], cs = -LOG2E * s, s2 = s * s;
;                 f32x4 o[2];
; #pragma unroll
;                 for (int n = 0; n < 2; ++n) { const f32x4 g = acc[ai][0][m][n], gu = acc[ai][0][m][n] * acc[ai][1][m][n]; f32x4 r;
; #pragma unroll
;                     for (int e = 0; e < 4; ++e) r[e] = gu[e] * (s2 * __builtin_amdgcn_rcpf(1.f + __builtin_amdgcn_exp2f(cs * g[e])));
;                     o[n] = r; }
;                 *(u32x4*)(H + (size_t)row * ldc + (u.c0 >> 1) + wc * 32 + 8 * fq) = pack8(o[0], o[1]); }
.Lp8_tail:
	v_mul_f32_e32 v24, v28, v24
	v_mul_f32_e32 v25, v29, v25
	v_mul_f32_e32 v26, v30, v26
	v_mul_f32_e32 v27, v31, v27
	v_mul_f32_e32 v16, v20, v16
	v_mul_f32_e32 v17, v21, v17
	v_mul_f32_e32 v18, v22, v18
	v_mul_f32_e32 v19, v23, v19
	v_mul_f32_e32 v248, 0xbfb8aa3b, v179
	v_mul_f32_e32 v250, v179, v179
	v_mul_f32_e32 v28, v28, v248
	v_mul_f32_e32 v29, v29, v248
	v_mul_f32_e32 v30, v30, v248
	v_mul_f32_e32 v31, v31, v248
	v_mul_f32_e32 v20, v20, v248
	v_mul_f32_e32 v21, v21, v248
	v_mul_f32_e32 v22, v22, v248
	v_mul_f32_e32 v23, v23, v248
	v_exp_f32_e32 v28, v28
	v_exp_f32_e32 v29, v29
	v_exp_f32_e32 v30, v30
	v_exp_f32_e32 v31, v31
	v_exp_f32_e32 v20, v20
	v_exp_f32_e32 v21, v21
	v_exp_f32_e32 v22, v22
	v_exp_f32_e32 v23, v23
	v_add_f32_e32 v28, 1.0, v28
	v_add_f32_e32 v29, 1.0, v29
	v_add_f32_e32 v30, 1.0, v30
	v_add_f32_e32 v31, 1.0, v31
	v_add_f32_e32 v20, 1.0, v20
	v_add_f32_e32 v21, 1.0, v21
	v_add_f32_e32 v22, 1.0, v22
	v_add_f32_e32 v23, 1.0, v23
	v_rcp_f32_e32 v28, v28
	v_rcp_f32_e32 v29, v29
	v_rcp_f32_e32 v30, v30
	v_rcp_f32_e32 v31, v31
	v_rcp_f32_e32 v20, v20
	v_rcp_f32_e32 v21, v21
	v_rcp_f32_e32 v22, v22
	v_rcp_f32_e32 v23, v23
	v_mul_f32_e32 v28, v250, v28
	v_mul_f32_e32 v29, v250, v29
	v_mul_f32_e32 v30, v250, v30
	v_mul_f32_e32 v31, v250, v31
	v_mul_f32_e32 v20, v250, v20
	v_mul_f32_e32 v21, v250, v21
	v_mul_f32_e32 v22, v250, v22
	v_mul_f32_e32 v23, v250, v23
	v_mul_f32_e32 v24, v24, v28
	v_mul_f32_e32 v25, v25, v29
	v_mul_f32_e32 v26, v26, v30
	v_mul_f32_e32 v27, v27, v31
	v_mul_f32_e32 v16, v16, v20
	v_mul_f32_e32 v17, v17, v21
	v_mul_f32_e32 v18, v18, v22
	v_mul_f32_e32 v19, v19, v23
	v_cvt_pk_bf16_f32 v28, v24, v25
	v_cvt_pk_bf16_f32 v29, v26, v27
	v_cvt_pk_bf16_f32 v30, v16, v17
	v_cvt_pk_bf16_f32 v31, v18, v19
	global_store_dwordx4 v[252:253], v[28:31], off
	v_add_co_u32_e32 v252, vcc, 0x16000, v252
	s_nop 1
	v_addc_co_u32_e32 v253, vcc, 0, v253, vcc
	v_mul_f32_e32 v8, v12, v8
	v_mul_f32_e32 v9, v13, v9
	v_mul_f32_e32 v10, v14, v10
	v_mul_f32_e32 v11, v15, v11
	v_mul_f32_e32 v0, v4, v0
	v_mul_f32_e32 v1, v5, v1
	v_mul_f32_e32 v2, v6, v2
	v_mul_f32_e32 v3, v7, v3
	v_mul_f32_e32 v248, 0xbfb8aa3b, v221
	v_mul_f32_e32 v250, v221, v221
	v_mul_f32_e32 v12, v12, v248
	v_mul_f32_e32 v13, v13, v248
	v_mul_f32_e32 v14, v14, v248
	v_mul_f32_e32 v15, v15, v248
	v_mul_f32_e32 v4, v4, v248
	v_mul_f32_e32 v5, v5, v248
	v_mul_f32_e32 v6, v6, v248
	v_mul_f32_e32 v7, v7, v248
	v_exp_f32_e32 v12, v12
	v_exp_f32_e32 v13, v13
	v_exp_f32_e32 v14, v14
	v_exp_f32_e32 v15, v15
	v_exp_f32_e32 v4, v4
	v_exp_f32_e32 v5, v5
	v_exp_f32_e32 v6, v6
	v_exp_f32_e32 v7, v7
	v_add_f32_e32 v12, 1.0, v12
	v_add_f32_e32 v13, 1.0, v13
	v_add_f32_e32 v14, 1.0, v14
	v_add_f32_e32 v15, 1.0, v15
	v_add_f32_e32 v4, 1.0, v4
	v_add_f32_e32 v5, 1.0, v5
	v_add_f32_e32 v6, 1.0, v6
	v_add_f32_e32 v7, 1.0, v7
	v_rcp_f32_e32 v12, v12
	v_rcp_f32_e32 v13, v13
	v_rcp_f32_e32 v14, v14
	v_rcp_f32_e32 v15, v15
	v_rcp_f32_e32 v4, v4
	v_rcp_f32_e32 v5, v5
	v_rcp_f32_e32 v6, v6
	v_rcp_f32_e32 v7, v7
	v_mul_f32_e32 v12, v250, v12
	v_mul_f32_e32 v13, v250, v13
	v_mul_f32_e32 v14, v250, v14
	v_mul_f32_e32 v15, v250, v15
	v_mul_f32_e32 v4, v250, v4
	v_mul_f32_e32 v5, v250, v5
	v_mul_f32_e32 v6, v250, v6
	v_mul_f32_e32 v7, v250, v7
	v_mul_f32_e32 v8, v8, v12
	v_mul_f32_e32 v9, v9, v13
	v_mul_f32_e32 v10, v10, v14
	v_mul_f32_e32 v11, v11, v15
	v_mul_f32_e32 v0, v0, v4
	v_mul_f32_e32 v1, v1, v5
	v_mul_f32_e32 v2, v2, v6
	v_mul_f32_e32 v3, v3, v7
	v_cvt_pk_bf16_f32 v12, v8, v9
	v_cvt_pk_bf16_f32 v13, v10, v11
	v_cvt_pk_bf16_f32 v14, v0, v1
	v_cvt_pk_bf16_f32 v15, v2, v3
	global_store_dwordx4 v[252:253], v[12:15], off
